# in_cd epilogue: rotary table loads hoisted ahead of stores, counted waits (no store round-trips waited)
# speedup vs baseline: 1.0038x; 1.0038x over previous
;     __device__ __forceinline__ void operator()(const f32x4 (&acc)[2][2][4][2], const pg8::Unit& u, int wr, int wc, int fr, int fq, int buf) const {
;     ...
; #pragma unroll
;             for (int ai = 0; ai < 2; ++ai)
; #pragma unroll
;                 for (int m = 0; m < 4; ++m) {
;                     const int rl = ai * 128 + m * 16 + rloc0; const size_t row = (size_t)u.pm * 256 + rl;
;                     f32x4 c4 = {}, s4 = {};
;                     if (roped && lat) { const int t = (jt - 1) * 256 + rl; const int ti = t * 64 + 32 * (wc >> 1) + 16 * (wc & 1) + 4 * fq; c4 = *(const f32x4*)(cs + ti); s4 = *(const f32x4*)(sn + ti); }
.LBB0_1718:
	v_add_u32_e32 v164, s40, v135
	s_lshl_b32 s59, s59, 8
	v_lshl_add_u32 v192, v134, 2, s47
	v_mov_b32_e32 v134, 0
	v_cndmask_b32_e64 v135, 0, 1, s[8:9]
	s_addk_i32 s59, 0xff00
	v_cmp_ne_u32_e64 s[6:7], 1, v135
	s_andn2_b64 vcc, exec, s[8:9]
	v_mov_b32_e32 v135, v134
	v_mov_b32_e32 v136, v134
	v_mov_b32_e32 v137, v134
	v_mov_b32_e32 v138, v134
	v_mov_b32_e32 v139, v134
	v_mov_b32_e32 v140, v134
	v_mov_b32_e32 v141, v134
	s_cbranch_vccnz .LBB0_1720
	v_add_u32_e32 v204, s59, v164
	v_lshl_add_u32 v204, v204, 6, v192
	v_ashrrev_i32_e32 v205, 31, v204
	v_lshlrev_b64 v[204:205], 2, v[204:205]
	v_lshl_add_u64 v[208:209], s[22:23], 0, v[204:205]
	v_lshl_add_u64 v[204:205], s[20:21], 0, v[204:205]
	global_load_dwordx4 v[204:207], v[204:205], off
	s_nop 0
	global_load_dwordx4 v[208:211], v[208:209], off
	v_add_u32_e32 v212, 16, v164
	v_add_u32_e32 v212, s59, v212
	v_lshl_add_u32 v212, v212, 6, v192
	v_ashrrev_i32_e32 v213, 31, v212
	v_lshlrev_b64 v[212:213], 2, v[212:213]
	v_lshl_add_u64 v[216:217], s[22:23], 0, v[212:213]
	v_lshl_add_u64 v[212:213], s[20:21], 0, v[212:213]
	global_load_dwordx4 v[212:215], v[212:213], off
	s_nop 0
	global_load_dwordx4 v[216:219], v[216:217], off
	v_add_u32_e32 v220, 32, v164
	v_add_u32_e32 v220, s59, v220
	v_lshl_add_u32 v220, v220, 6, v192
	v_ashrrev_i32_e32 v221, 31, v220
	v_lshlrev_b64 v[220:221], 2, v[220:221]
	v_lshl_add_u64 v[224:225], s[22:23], 0, v[220:221]
	v_lshl_add_u64 v[220:221], s[20:21], 0, v[220:221]
	global_load_dwordx4 v[220:223], v[220:221], off
	s_nop 0
	global_load_dwordx4 v[224:227], v[224:225], off
	v_add_u32_e32 v228, 48, v164
	v_add_u32_e32 v228, s59, v228
	v_lshl_add_u32 v228, v228, 6, v192
	v_ashrrev_i32_e32 v229, 31, v228
	v_lshlrev_b64 v[228:229], 2, v[228:229]
	v_lshl_add_u64 v[232:233], s[22:23], 0, v[228:229]
	v_lshl_add_u64 v[228:229], s[20:21], 0, v[228:229]
	global_load_dwordx4 v[228:231], v[228:229], off
	s_nop 0
	global_load_dwordx4 v[232:235], v[232:233], off
	v_add_u32_e32 v236, 128, v164
	v_add_u32_e32 v236, s59, v236
	v_lshl_add_u32 v236, v236, 6, v192
	v_ashrrev_i32_e32 v237, 31, v236
	v_lshlrev_b64 v[236:237], 2, v[236:237]
	v_lshl_add_u64 v[240:241], s[22:23], 0, v[236:237]
	v_lshl_add_u64 v[236:237], s[20:21], 0, v[236:237]
	global_load_dwordx4 v[236:239], v[236:237], off
	s_nop 0
	global_load_dwordx4 v[240:243], v[240:241], off
	v_add_u32_e32 v244, 144, v164
	v_add_u32_e32 v244, s59, v244
	v_lshl_add_u32 v244, v244, 6, v192
	v_ashrrev_i32_e32 v245, 31, v244
	v_lshlrev_b64 v[244:245], 2, v[244:245]
	v_lshl_add_u64 v[248:249], s[22:23], 0, v[244:245]
	v_lshl_add_u64 v[244:245], s[20:21], 0, v[244:245]
	global_load_dwordx4 v[244:247], v[244:245], off
	s_nop 0
	global_load_dwordx4 v[248:251], v[248:249], off

; __device__ __forceinline__ void store8(bf16_t* p, const f32x4& a, const f32x4& b) { u32x4 w; w.x = pk2(a[0], a[1]); w.y = pk2(a[2], a[3]); w.z = pk2(b[0], b[1]); w.w = pk2(b[2], b[3]); *(u32x4*)p = w; }
;     __device__ __forceinline__ void operator()(const f32x4 (&acc)[2][2][4][2], const pg8::Unit& u, int wr, int wc, int fr, int fq, int buf) const {
;     ...
;                     for (int bj = 0; bj < 2; ++bj) {
;                         const int hh = (grp >= 5) ? bj : (pn & 1) * 2 + bj;
;                         f32x4 v0 = acc[ai][bj][m][0], v1 = acc[ai][bj][m][1];
;                         if (hnorm) { const float r = rs[bj][ai][m];
; #pragma unroll
;                             for (int c = 0; c < 4; ++c) { v0[c] = v0[c] * r * gw[c]; v1[c] = v1[c] * r * gw[4 + c]; } }
;                         if (grp == 1) { v0 = v0 * 0.08838834764831845f; v1 = v1 * 0.08838834764831845f; }
;                         if (roped && lat) {
;                             f32x4 o0, o1;
;                             o0[0] = v0[0] * c4[0] - v0[1] * s4[0]; o0[1] = v0[1] * c4[0] + v0[0] * s4[0]; o0[2] = v0[2] * c4[1] - v0[3] * s4[1]; o0[3] = v0[3] * c4[1] + v0[2] * s4[1];
;                             o1[0] = v1[0] * c4[2] - v1[1] * s4[2]; o1[1] = v1[1] * c4[2] + v1[0] * s4[2]; o1[2] = v1[2] * c4[3] - v1[3] * s4[3]; o1[3] = v1[3] * c4[3] + v1[2] * s4[3];
;                             v0 = o0; v1 = o1;
;                         }
;                         bf16_t* dst = dbase + row * dld + 128 * hh + dloc;
;                         store8(dst, v0, v1);
.LBB0_1722:
	s_cmp_eq_u32 s61, 1
	v_pk_mul_f32 v[184:185], v[128:129], s[56:57] op_sel_hi:[1,0]
	v_pk_mul_f32 v[194:195], v[126:127], s[56:57] op_sel_hi:[1,0]
	v_pk_mul_f32 v[182:183], v[132:133], s[56:57] op_sel_hi:[1,0]
	v_pk_mul_f32 v[196:197], v[130:131], s[56:57] op_sel_hi:[1,0]
	s_cselect_b64 s[8:9], -1, 0
	v_cndmask_b32_e64 v131, v131, v197, s[8:9]
	v_cndmask_b32_e64 v130, v130, v196, s[8:9]
	v_cndmask_b32_e64 v183, v133, v183, s[8:9]
	v_cndmask_b32_e64 v182, v132, v182, s[8:9]
	v_cndmask_b32_e64 v133, v127, v195, s[8:9]
	v_cndmask_b32_e64 v132, v126, v194, s[8:9]
	v_cndmask_b32_e64 v185, v129, v185, s[8:9]
	s_and_b64 vcc, exec, s[6:7]
	v_cndmask_b32_e64 v184, v128, v184, s[8:9]
	s_cbranch_vccnz .LBB0_1724
	s_waitcnt vmcnt(0)
	v_pk_mul_f32 v[128:129], v[208:209], v[132:133] op_sel:[0,1] op_sel_hi:[0,0]
	v_pk_mul_f32 v[126:127], v[204:205], v[132:133]
	v_pk_fma_f32 v[132:133], v[204:205], v[132:133], v[128:129] op_sel_hi:[0,1,1]
	v_mov_b32_e32 v194, v205
	v_mov_b32_e32 v195, v209
	v_mul_f32_e32 v132, v209, v185
	v_pk_fma_f32 v[194:195], v[194:195], v[184:185], v[132:133] op_sel_hi:[1,1,0] neg_lo:[0,0,1] neg_hi:[0,0,1]
	v_mov_b32_e32 v196, v209
	v_mov_b32_e32 v197, v205
	v_mul_f32_e32 v132, v205, v185
	v_pk_mul_f32 v[198:199], v[210:211], v[130:131] op_sel:[0,1] op_sel_hi:[0,0]
	v_pk_fma_f32 v[196:197], v[196:197], v[184:185], v[132:133] op_sel_hi:[1,1,0]
	v_pk_mul_f32 v[184:185], v[206:207], v[130:131]
	v_pk_fma_f32 v[130:131], v[206:207], v[130:131], v[198:199] op_sel_hi:[0,1,1]
	v_mov_b32_e32 v200, v207
	v_mov_b32_e32 v201, v211
	v_mul_f32_e32 v130, v211, v183
	v_pk_fma_f32 v[200:201], v[200:201], v[182:183], v[130:131] op_sel_hi:[1,1,0] neg_lo:[0,0,1] neg_hi:[0,0,1]
	v_mov_b32_e32 v202, v211
	v_mov_b32_e32 v203, v207
	v_mul_f32_e32 v130, v207, v183
	v_pk_fma_f32 v[202:203], v[202:203], v[182:183], v[130:131] op_sel_hi:[1,1,0]
	v_sub_f32_e32 v130, v184, v198
	v_sub_f32_e32 v132, v126, v128
	v_mov_b32_e32 v182, v200
	v_mov_b32_e32 v183, v202
	v_mov_b32_e32 v184, v194
	v_mov_b32_e32 v185, v196

; __device__ __forceinline__ void store8(bf16_t* p, const f32x4& a, const f32x4& b) { u32x4 w; w.x = pk2(a[0], a[1]); w.y = pk2(a[2], a[3]); w.z = pk2(b[0], b[1]); w.w = pk2(b[2], b[3]); *(u32x4*)p = w; }
;     __device__ __forceinline__ void operator()(const f32x4 (&acc)[2][2][4][2], const pg8::Unit& u, int wr, int wc, int fr, int fq, int buf) const {
;     ...
;                     if (roped && lat) { const int t = (jt - 1) * 256 + rl; const int ti = t * 64 + 32 * (wc >> 1) + 16 * (wc & 1) + 4 * fq; c4 = *(const f32x4*)(cs + ti); s4 = *(const f32x4*)(sn + ti); }
; #pragma unroll
;                     for (int bj = 0; bj < 2; ++bj) {
;                         const int hh = (grp >= 5) ? bj : (pn & 1) * 2 + bj;
;                         f32x4 v0 = acc[ai][bj][m][0], v1 = acc[ai][bj][m][1];
;                         if (hnorm) { const float r = rs[bj][ai][m];
; #pragma unroll
;                             for (int c = 0; c < 4; ++c) { v0[c] = v0[c] * r * gw[c]; v1[c] = v1[c] * r * gw[4 + c]; } }
;                         if (grp == 1) { v0 = v0 * 0.08838834764831845f; v1 = v1 * 0.08838834764831845f; }
;                         if (roped && lat) {
;                             f32x4 o0, o1;
;                             o0[0] = v0[0] * c4[0] - v0[1] * s4[0]; o0[1] = v0[1] * c4[0] + v0[0] * s4[0]; o0[2] = v0[2] * c4[1] - v0[3] * s4[1]; o0[3] = v0[3] * c4[1] + v0[2] * s4[1];
;                             o1[0] = v1[0] * c4[2] - v1[1] * s4[2]; o1[1] = v1[1] * c4[2] + v1[0] * s4[2]; o1[2] = v1[2] * c4[3] - v1[3] * s4[3]; o1[3] = v1[3] * c4[3] + v1[2] * s4[3];
;                             v0 = o0; v1 = o1;
;                         }
;                         bf16_t* dst = dbase + row * dld + 128 * hh + dloc;
;                         store8(dst, v0, v1);
.LBB0_1726:
	v_pk_mul_f32 v[130:131], v[120:121], s[56:57] op_sel_hi:[1,0]
	v_pk_mul_f32 v[132:133], v[118:119], s[56:57] op_sel_hi:[1,0]
	v_pk_mul_f32 v[180:181], v[124:125], s[56:57] op_sel_hi:[1,0]
	v_pk_mul_f32 v[182:183], v[122:123], s[56:57] op_sel_hi:[1,0]
	v_cndmask_b32_e64 v125, v125, v181, s[8:9]
	v_cndmask_b32_e64 v124, v124, v180, s[8:9]
	v_cndmask_b32_e64 v123, v123, v183, s[8:9]
	v_cndmask_b32_e64 v122, v122, v182, s[8:9]
	v_cndmask_b32_e64 v121, v121, v131, s[8:9]
	v_cndmask_b32_e64 v120, v120, v130, s[8:9]
	v_cndmask_b32_e64 v119, v119, v133, s[8:9]
	s_and_b64 vcc, exec, s[6:7]
	v_cndmask_b32_e64 v118, v118, v132, s[8:9]
	s_cbranch_vccnz .LBB0_1728
	v_pk_mul_f32 v[132:133], v[208:209], v[118:119] op_sel:[0,1] op_sel_hi:[0,0]
	v_pk_mul_f32 v[130:131], v[204:205], v[118:119]
	v_pk_fma_f32 v[118:119], v[204:205], v[118:119], v[132:133] op_sel_hi:[0,1,1]
	v_mov_b32_e32 v208, v205
	v_mul_f32_e32 v118, v209, v121
	v_pk_fma_f32 v[180:181], v[208:209], v[120:121], v[118:119] op_sel_hi:[1,1,0] neg_lo:[0,0,1] neg_hi:[0,0,1]
	v_mov_b32_e32 v204, v209
	v_mul_f32_e32 v118, v205, v121
	v_pk_fma_f32 v[204:205], v[204:205], v[120:121], v[118:119] op_sel_hi:[1,1,0]
	v_pk_mul_f32 v[208:209], v[210:211], v[122:123] op_sel:[0,1] op_sel_hi:[0,0]
	v_mov_b32_e32 v210, v207
	v_mul_f32_e32 v118, v211, v125
	v_pk_mul_f32 v[120:121], v[206:207], v[122:123]
	v_pk_fma_f32 v[122:123], v[206:207], v[122:123], v[208:209] op_sel_hi:[0,1,1]
	v_pk_fma_f32 v[182:183], v[210:211], v[124:125], v[118:119] op_sel_hi:[1,1,0] neg_lo:[0,0,1] neg_hi:[0,0,1]
	v_mov_b32_e32 v206, v211
	v_mul_f32_e32 v118, v207, v125
	v_pk_fma_f32 v[206:207], v[206:207], v[124:125], v[118:119] op_sel_hi:[1,1,0]
	v_sub_f32_e32 v122, v120, v208
	v_sub_f32_e32 v118, v130, v132
	v_mov_b32_e32 v124, v182
	v_mov_b32_e32 v125, v206
	v_mov_b32_e32 v120, v180
	v_mov_b32_e32 v121, v204
	v_add_u32_e32 v204, 160, v164
	v_add_u32_e32 v204, s59, v204
	v_lshl_add_u32 v204, v204, 6, v192
	v_ashrrev_i32_e32 v205, 31, v204
	v_lshlrev_b64 v[204:205], 2, v[204:205]
	v_lshl_add_u64 v[208:209], s[22:23], 0, v[204:205]
	v_lshl_add_u64 v[204:205], s[20:21], 0, v[204:205]
	global_load_dwordx4 v[204:207], v[204:205], off
	s_nop 0
	global_load_dwordx4 v[208:211], v[208:209], off
.LBB0_1728:
	v_cvt_pk_bf16_f32 v118, v118, v119
	v_cvt_pk_bf16_f32 v119, v120, v121
	v_cvt_pk_bf16_f32 v120, v122, v123
	v_cvt_pk_bf16_f32 v121, v124, v125
	global_store_dwordx4 v[128:129], v[118:121], off offset:256
	v_add_u32_e32 v128, 16, v164
.LBB0_1730:
	s_and_b64 vcc, exec, s[4:5]
	s_cbranch_vccnz .LBB0_1732
	v_pk_mul_f32 v[112:113], v[112:113], v[176:177] op_sel:[0,1]
	v_pk_mul_f32 v[110:111], v[110:111], v[176:177] op_sel:[0,1]
	v_pk_mul_f32 v[116:117], v[116:117], v[176:177] op_sel:[0,1]
	v_pk_mul_f32 v[114:115], v[114:115], v[176:177] op_sel:[0,1]
	v_pk_mul_f32 v[110:111], v[110:111], v[162:163]
	v_pk_mul_f32 v[112:113], v[112:113], v[98:99]
	v_pk_mul_f32 v[114:115], v[114:115], v[160:161]
	v_pk_mul_f32 v[116:117], v[116:117], v[100:101]
.LBB0_1732:
	v_pk_mul_f32 v[130:131], v[112:113], s[56:57] op_sel_hi:[1,0]
	v_pk_mul_f32 v[132:133], v[110:111], s[56:57] op_sel_hi:[1,0]
	v_pk_mul_f32 v[134:135], v[116:117], s[56:57] op_sel_hi:[1,0]
	v_pk_mul_f32 v[136:137], v[114:115], s[56:57] op_sel_hi:[1,0]
	v_cndmask_b32_e64 v117, v117, v135, s[8:9]
	v_cndmask_b32_e64 v116, v116, v134, s[8:9]
	v_cndmask_b32_e64 v115, v115, v137, s[8:9]
	v_cndmask_b32_e64 v114, v114, v136, s[8:9]
	v_cndmask_b32_e64 v131, v113, v131, s[8:9]
	v_cndmask_b32_e64 v130, v112, v130, s[8:9]
	v_cndmask_b32_e64 v113, v111, v133, s[8:9]
	s_and_b64 vcc, exec, s[6:7]
	v_cndmask_b32_e64 v112, v110, v132, s[8:9]
	s_cbranch_vccnz .LBB0_1734
	v_pk_mul_f32 v[132:133], v[216:217], v[112:113] op_sel:[0,1] op_sel_hi:[0,0]
	v_pk_mul_f32 v[110:111], v[212:213], v[112:113]
	v_pk_fma_f32 v[112:113], v[212:213], v[112:113], v[132:133] op_sel_hi:[0,1,1]
	v_mov_b32_e32 v134, v213
	v_mov_b32_e32 v135, v217
	v_mul_f32_e32 v112, v217, v131
	v_pk_fma_f32 v[134:135], v[134:135], v[130:131], v[112:113] op_sel_hi:[1,1,0] neg_lo:[0,0,1] neg_hi:[0,0,1]
	v_mov_b32_e32 v136, v217
	v_mov_b32_e32 v137, v213
	v_mul_f32_e32 v112, v213, v131
	v_pk_fma_f32 v[136:137], v[136:137], v[130:131], v[112:113] op_sel_hi:[1,1,0]
	v_mov_b32_e32 v140, v215
	v_mov_b32_e32 v141, v219
	v_mul_f32_e32 v112, v219, v117
	v_pk_mul_f32 v[138:139], v[218:219], v[114:115] op_sel:[0,1] op_sel_hi:[0,0]
	v_pk_fma_f32 v[140:141], v[140:141], v[116:117], v[112:113] op_sel_hi:[1,1,0] neg_lo:[0,0,1] neg_hi:[0,0,1]
	v_mov_b32_e32 v176, v219
	v_mov_b32_e32 v177, v215
	v_mul_f32_e32 v112, v215, v117
	v_pk_mul_f32 v[130:131], v[214:215], v[114:115]
	v_pk_fma_f32 v[114:115], v[214:215], v[114:115], v[138:139] op_sel_hi:[0,1,1]
	v_pk_fma_f32 v[176:177], v[176:177], v[116:117], v[112:113] op_sel_hi:[1,1,0]
	v_sub_f32_e32 v114, v130, v138
	v_sub_f32_e32 v112, v110, v132
	v_mov_b32_e32 v116, v140
	v_mov_b32_e32 v117, v176
	v_mov_b32_e32 v130, v134
	v_mov_b32_e32 v131, v136

; __device__ __forceinline__ void store8(bf16_t* p, const f32x4& a, const f32x4& b) { u32x4 w; w.x = pk2(a[0], a[1]); w.y = pk2(a[2], a[3]); w.z = pk2(b[0], b[1]); w.w = pk2(b[2], b[3]); *(u32x4*)p = w; }
;     __device__ __forceinline__ void operator()(const f32x4 (&acc)[2][2][4][2], const pg8::Unit& u, int wr, int wc, int fr, int fq, int buf) const {
;     ...
;                     if (roped && lat) { const int t = (jt - 1) * 256 + rl; const int ti = t * 64 + 32 * (wc >> 1) + 16 * (wc & 1) + 4 * fq; c4 = *(const f32x4*)(cs + ti); s4 = *(const f32x4*)(sn + ti); }
; #pragma unroll
;                     for (int bj = 0; bj < 2; ++bj) {
;                         const int hh = (grp >= 5) ? bj : (pn & 1) * 2 + bj;
;                         f32x4 v0 = acc[ai][bj][m][0], v1 = acc[ai][bj][m][1];
;                         if (hnorm) { const float r = rs[bj][ai][m];
; #pragma unroll
;                             for (int c = 0; c < 4; ++c) { v0[c] = v0[c] * r * gw[c]; v1[c] = v1[c] * r * gw[4 + c]; } }
;                         if (grp == 1) { v0 = v0 * 0.08838834764831845f; v1 = v1 * 0.08838834764831845f; }
;                         if (roped && lat) {
;                             f32x4 o0, o1;
;                             o0[0] = v0[0] * c4[0] - v0[1] * s4[0]; o0[1] = v0[1] * c4[0] + v0[0] * s4[0]; o0[2] = v0[2] * c4[1] - v0[3] * s4[1]; o0[3] = v0[3] * c4[1] + v0[2] * s4[1];
;                             o1[0] = v1[0] * c4[2] - v1[1] * s4[2]; o1[1] = v1[1] * c4[2] + v1[0] * s4[2]; o1[2] = v1[2] * c4[3] - v1[3] * s4[3]; o1[3] = v1[3] * c4[3] + v1[2] * s4[3];
;                             v0 = o0; v1 = o1;
;                         }
;                         bf16_t* dst = dbase + row * dld + 128 * hh + dloc;
;                         store8(dst, v0, v1);
.LBB0_1736:
	s_nop 0
	v_pk_mul_f32 v[112:113], v[104:105], s[56:57] op_sel_hi:[1,0]
	v_pk_mul_f32 v[114:115], v[102:103], s[56:57] op_sel_hi:[1,0]
	v_pk_mul_f32 v[116:117], v[108:109], s[56:57] op_sel_hi:[1,0]
	v_pk_mul_f32 v[128:129], v[106:107], s[56:57] op_sel_hi:[1,0]
	v_cndmask_b32_e64 v109, v109, v117, s[8:9]
	v_cndmask_b32_e64 v108, v108, v116, s[8:9]
	v_cndmask_b32_e64 v107, v107, v129, s[8:9]
	v_cndmask_b32_e64 v106, v106, v128, s[8:9]
	v_cndmask_b32_e64 v105, v105, v113, s[8:9]
	v_cndmask_b32_e64 v104, v104, v112, s[8:9]
	v_cndmask_b32_e64 v103, v103, v115, s[8:9]
	s_and_b64 vcc, exec, s[6:7]
	v_cndmask_b32_e64 v102, v102, v114, s[8:9]
	s_cbranch_vccnz .LBB0_1738
	v_pk_mul_f32 v[114:115], v[216:217], v[102:103] op_sel:[0,1] op_sel_hi:[0,0]
	v_pk_mul_f32 v[112:113], v[212:213], v[102:103]
	v_pk_fma_f32 v[102:103], v[212:213], v[102:103], v[114:115] op_sel_hi:[0,1,1]
	v_mov_b32_e32 v216, v213
	v_mul_f32_e32 v102, v217, v105
	v_pk_fma_f32 v[116:117], v[216:217], v[104:105], v[102:103] op_sel_hi:[1,1,0] neg_lo:[0,0,1] neg_hi:[0,0,1]
	v_mov_b32_e32 v212, v217
	v_mul_f32_e32 v102, v213, v105
	v_pk_fma_f32 v[212:213], v[212:213], v[104:105], v[102:103] op_sel_hi:[1,1,0]
	v_pk_mul_f32 v[216:217], v[218:219], v[106:107] op_sel:[0,1] op_sel_hi:[0,0]
	v_mov_b32_e32 v218, v215
	v_mul_f32_e32 v102, v219, v109
	v_pk_mul_f32 v[104:105], v[214:215], v[106:107]
	v_pk_fma_f32 v[106:107], v[214:215], v[106:107], v[216:217] op_sel_hi:[0,1,1]
	v_pk_fma_f32 v[128:129], v[218:219], v[108:109], v[102:103] op_sel_hi:[1,1,0] neg_lo:[0,0,1] neg_hi:[0,0,1]
	v_mov_b32_e32 v214, v219
	v_mul_f32_e32 v102, v215, v109
	v_pk_fma_f32 v[214:215], v[214:215], v[108:109], v[102:103] op_sel_hi:[1,1,0]
	v_sub_f32_e32 v106, v104, v216
	v_sub_f32_e32 v102, v112, v114
	v_mov_b32_e32 v108, v128
	v_mov_b32_e32 v109, v214
	v_mov_b32_e32 v104, v116
	v_mov_b32_e32 v105, v212
	v_add_u32_e32 v212, 176, v164
	v_add_u32_e32 v212, s59, v212
	v_lshl_add_u32 v212, v212, 6, v192
	v_ashrrev_i32_e32 v213, 31, v212
	v_lshlrev_b64 v[212:213], 2, v[212:213]
	v_lshl_add_u64 v[216:217], s[22:23], 0, v[212:213]
	v_lshl_add_u64 v[212:213], s[20:21], 0, v[212:213]
	global_load_dwordx4 v[212:215], v[212:213], off
	s_nop 0
	global_load_dwordx4 v[216:219], v[216:217], off
.LBB0_1738:
	v_cvt_pk_bf16_f32 v102, v102, v103
	v_cvt_pk_bf16_f32 v103, v104, v105
	v_cvt_pk_bf16_f32 v104, v106, v107
	v_cvt_pk_bf16_f32 v105, v108, v109
	global_store_dwordx4 v[110:111], v[102:105], off offset:256
	v_add_u32_e32 v110, 32, v164
.LBB0_1740:
	s_and_b64 vcc, exec, s[4:5]
	s_cbranch_vccnz .LBB0_1742
	v_pk_mul_f32 v[92:93], v[92:93], v[172:173] op_sel_hi:[1,0]
	v_pk_mul_f32 v[90:91], v[90:91], v[172:173] op_sel_hi:[1,0]
	v_pk_mul_f32 v[96:97], v[96:97], v[172:173] op_sel_hi:[1,0]
	v_pk_mul_f32 v[94:95], v[94:95], v[172:173] op_sel_hi:[1,0]
	v_pk_mul_f32 v[90:91], v[90:91], v[162:163]
	v_pk_mul_f32 v[92:93], v[92:93], v[98:99]
	v_pk_mul_f32 v[94:95], v[94:95], v[160:161]
	v_pk_mul_f32 v[96:97], v[96:97], v[100:101]
.LBB0_1742:
	v_pk_mul_f32 v[112:113], v[92:93], s[56:57] op_sel_hi:[1,0]
	v_pk_mul_f32 v[114:115], v[90:91], s[56:57] op_sel_hi:[1,0]
	v_pk_mul_f32 v[116:117], v[96:97], s[56:57] op_sel_hi:[1,0]
	v_pk_mul_f32 v[118:119], v[94:95], s[56:57] op_sel_hi:[1,0]
	v_cndmask_b32_e64 v97, v97, v117, s[8:9]
	v_cndmask_b32_e64 v96, v96, v116, s[8:9]
	v_cndmask_b32_e64 v95, v95, v119, s[8:9]
	v_cndmask_b32_e64 v94, v94, v118, s[8:9]
	v_cndmask_b32_e64 v113, v93, v113, s[8:9]
	v_cndmask_b32_e64 v112, v92, v112, s[8:9]
	v_cndmask_b32_e64 v93, v91, v115, s[8:9]
	s_and_b64 vcc, exec, s[6:7]
	v_cndmask_b32_e64 v92, v90, v114, s[8:9]
	s_cbranch_vccnz .LBB0_1744
	v_pk_mul_f32 v[114:115], v[224:225], v[92:93] op_sel:[0,1] op_sel_hi:[0,0]
	v_pk_mul_f32 v[90:91], v[220:221], v[92:93]
	v_pk_fma_f32 v[92:93], v[220:221], v[92:93], v[114:115] op_sel_hi:[0,1,1]
	v_mov_b32_e32 v116, v221
	v_mov_b32_e32 v117, v225
	v_mul_f32_e32 v92, v225, v113
	v_pk_fma_f32 v[116:117], v[116:117], v[112:113], v[92:93] op_sel_hi:[1,1,0] neg_lo:[0,0,1] neg_hi:[0,0,1]
	v_mov_b32_e32 v118, v225
	v_mov_b32_e32 v119, v221
	v_mul_f32_e32 v92, v221, v113
	v_pk_fma_f32 v[118:119], v[118:119], v[112:113], v[92:93] op_sel_hi:[1,1,0]
	v_mov_b32_e32 v122, v223
	v_mov_b32_e32 v123, v227
	v_mul_f32_e32 v92, v227, v97
	v_pk_mul_f32 v[120:121], v[226:227], v[94:95] op_sel:[0,1] op_sel_hi:[0,0]
	v_pk_fma_f32 v[122:123], v[122:123], v[96:97], v[92:93] op_sel_hi:[1,1,0] neg_lo:[0,0,1] neg_hi:[0,0,1]
	v_mov_b32_e32 v124, v227
	v_mov_b32_e32 v125, v223
	v_mul_f32_e32 v92, v223, v97
	v_pk_mul_f32 v[112:113], v[222:223], v[94:95]
	v_pk_fma_f32 v[94:95], v[222:223], v[94:95], v[120:121] op_sel_hi:[0,1,1]
	v_pk_fma_f32 v[124:125], v[124:125], v[96:97], v[92:93] op_sel_hi:[1,1,0]
	v_sub_f32_e32 v94, v112, v120
	v_sub_f32_e32 v92, v90, v114
	v_mov_b32_e32 v96, v122
	v_mov_b32_e32 v97, v124
	v_mov_b32_e32 v112, v116
	v_mov_b32_e32 v113, v118

; __device__ __forceinline__ void store8(bf16_t* p, const f32x4& a, const f32x4& b) { u32x4 w; w.x = pk2(a[0], a[1]); w.y = pk2(a[2], a[3]); w.z = pk2(b[0], b[1]); w.w = pk2(b[2], b[3]); *(u32x4*)p = w; }
;     __device__ __forceinline__ void operator()(const f32x4 (&acc)[2][2][4][2], const pg8::Unit& u, int wr, int wc, int fr, int fq, int buf) const {
;     ...
;                     for (int bj = 0; bj < 2; ++bj) {
;                         const int hh = (grp >= 5) ? bj : (pn & 1) * 2 + bj;
;                         f32x4 v0 = acc[ai][bj][m][0], v1 = acc[ai][bj][m][1];
;                         if (hnorm) { const float r = rs[bj][ai][m];
; #pragma unroll
;                             for (int c = 0; c < 4; ++c) { v0[c] = v0[c] * r * gw[c]; v1[c] = v1[c] * r * gw[4 + c]; } }
;                         if (grp == 1) { v0 = v0 * 0.08838834764831845f; v1 = v1 * 0.08838834764831845f; }
;                         if (roped && lat) {
;                             f32x4 o0, o1;
;                             o0[0] = v0[0] * c4[0] - v0[1] * s4[0]; o0[1] = v0[1] * c4[0] + v0[0] * s4[0]; o0[2] = v0[2] * c4[1] - v0[3] * s4[1]; o0[3] = v0[3] * c4[1] + v0[2] * s4[1];
;                             o1[0] = v1[0] * c4[2] - v1[1] * s4[2]; o1[1] = v1[1] * c4[2] + v1[0] * s4[2]; o1[2] = v1[2] * c4[3] - v1[3] * s4[3]; o1[3] = v1[3] * c4[3] + v1[2] * s4[3];
;                             v0 = o0; v1 = o1;
;                         }
;                         bf16_t* dst = dbase + row * dld + 128 * hh + dloc;
;                         store8(dst, v0, v1);
.LBB0_1746:
	s_nop 0
	v_pk_mul_f32 v[92:93], v[84:85], s[56:57] op_sel_hi:[1,0]
	v_pk_mul_f32 v[94:95], v[82:83], s[56:57] op_sel_hi:[1,0]
	v_pk_mul_f32 v[96:97], v[88:89], s[56:57] op_sel_hi:[1,0]
	v_pk_mul_f32 v[110:111], v[86:87], s[56:57] op_sel_hi:[1,0]
	v_cndmask_b32_e64 v89, v89, v97, s[8:9]
	v_cndmask_b32_e64 v88, v88, v96, s[8:9]
	v_cndmask_b32_e64 v87, v87, v111, s[8:9]
	v_cndmask_b32_e64 v86, v86, v110, s[8:9]
	v_cndmask_b32_e64 v85, v85, v93, s[8:9]
	v_cndmask_b32_e64 v84, v84, v92, s[8:9]
	v_cndmask_b32_e64 v83, v83, v95, s[8:9]
	s_and_b64 vcc, exec, s[6:7]
	v_cndmask_b32_e64 v82, v82, v94, s[8:9]
	s_cbranch_vccnz .LBB0_1748
	v_pk_mul_f32 v[94:95], v[224:225], v[82:83] op_sel:[0,1] op_sel_hi:[0,0]
	v_pk_mul_f32 v[92:93], v[220:221], v[82:83]
	v_pk_fma_f32 v[82:83], v[220:221], v[82:83], v[94:95] op_sel_hi:[0,1,1]
	v_mov_b32_e32 v224, v221
	v_mul_f32_e32 v82, v225, v85
	v_pk_fma_f32 v[96:97], v[224:225], v[84:85], v[82:83] op_sel_hi:[1,1,0] neg_lo:[0,0,1] neg_hi:[0,0,1]
	v_mov_b32_e32 v220, v225
	v_mul_f32_e32 v82, v221, v85
	v_pk_fma_f32 v[220:221], v[220:221], v[84:85], v[82:83] op_sel_hi:[1,1,0]
	v_pk_mul_f32 v[224:225], v[226:227], v[86:87] op_sel:[0,1] op_sel_hi:[0,0]
	v_mov_b32_e32 v226, v223
	v_mul_f32_e32 v82, v227, v89
	v_pk_mul_f32 v[84:85], v[222:223], v[86:87]
	v_pk_fma_f32 v[86:87], v[222:223], v[86:87], v[224:225] op_sel_hi:[0,1,1]
	v_pk_fma_f32 v[110:111], v[226:227], v[88:89], v[82:83] op_sel_hi:[1,1,0] neg_lo:[0,0,1] neg_hi:[0,0,1]
	v_mov_b32_e32 v222, v227
	v_mul_f32_e32 v82, v223, v89
	v_pk_fma_f32 v[222:223], v[222:223], v[88:89], v[82:83] op_sel_hi:[1,1,0]
	v_sub_f32_e32 v86, v84, v224
	v_sub_f32_e32 v82, v92, v94
	v_mov_b32_e32 v88, v110
	v_mov_b32_e32 v89, v222
	v_mov_b32_e32 v84, v96
	v_mov_b32_e32 v85, v220
.LBB0_1748:
	v_cvt_pk_bf16_f32 v82, v82, v83
	v_cvt_pk_bf16_f32 v83, v84, v85
	v_cvt_pk_bf16_f32 v84, v86, v87
	v_cvt_pk_bf16_f32 v85, v88, v89
	global_store_dwordx4 v[90:91], v[82:85], off offset:256
	v_add_u32_e32 v90, 48, v164
.LBB0_1750:
	s_and_b64 vcc, exec, s[4:5]
	s_cbranch_vccnz .LBB0_1752
	v_pk_mul_f32 v[76:77], v[76:77], v[172:173] op_sel:[0,1]
	v_pk_mul_f32 v[74:75], v[74:75], v[172:173] op_sel:[0,1]
	v_pk_mul_f32 v[80:81], v[80:81], v[172:173] op_sel:[0,1]
	v_pk_mul_f32 v[78:79], v[78:79], v[172:173] op_sel:[0,1]
	v_pk_mul_f32 v[74:75], v[74:75], v[162:163]
	v_pk_mul_f32 v[76:77], v[76:77], v[98:99]
	v_pk_mul_f32 v[78:79], v[78:79], v[160:161]
	v_pk_mul_f32 v[80:81], v[80:81], v[100:101]
.LBB0_1752:
	v_pk_mul_f32 v[92:93], v[76:77], s[56:57] op_sel_hi:[1,0]
	v_pk_mul_f32 v[94:95], v[74:75], s[56:57] op_sel_hi:[1,0]
	v_pk_mul_f32 v[96:97], v[80:81], s[56:57] op_sel_hi:[1,0]
	v_pk_mul_f32 v[102:103], v[78:79], s[56:57] op_sel_hi:[1,0]
	v_cndmask_b32_e64 v81, v81, v97, s[8:9]
	v_cndmask_b32_e64 v80, v80, v96, s[8:9]
	v_cndmask_b32_e64 v79, v79, v103, s[8:9]
	v_cndmask_b32_e64 v78, v78, v102, s[8:9]
	v_cndmask_b32_e64 v93, v77, v93, s[8:9]
	v_cndmask_b32_e64 v92, v76, v92, s[8:9]
	v_cndmask_b32_e64 v77, v75, v95, s[8:9]
	s_and_b64 vcc, exec, s[6:7]
	v_cndmask_b32_e64 v76, v74, v94, s[8:9]
	s_cbranch_vccnz .LBB0_1754
	v_pk_mul_f32 v[94:95], v[232:233], v[76:77] op_sel:[0,1] op_sel_hi:[0,0]
	v_pk_mul_f32 v[74:75], v[228:229], v[76:77]
	v_pk_fma_f32 v[76:77], v[228:229], v[76:77], v[94:95] op_sel_hi:[0,1,1]
	v_mov_b32_e32 v96, v229
	v_mov_b32_e32 v97, v233
	v_mul_f32_e32 v76, v233, v93
	v_pk_fma_f32 v[96:97], v[96:97], v[92:93], v[76:77] op_sel_hi:[1,1,0] neg_lo:[0,0,1] neg_hi:[0,0,1]
	v_mov_b32_e32 v102, v233
	v_mov_b32_e32 v103, v229
	v_mul_f32_e32 v76, v229, v93
	v_pk_fma_f32 v[102:103], v[102:103], v[92:93], v[76:77] op_sel_hi:[1,1,0]
	v_mov_b32_e32 v106, v231
	v_mov_b32_e32 v107, v235
	v_mul_f32_e32 v76, v235, v81
	v_pk_mul_f32 v[104:105], v[234:235], v[78:79] op_sel:[0,1] op_sel_hi:[0,0]
	v_pk_fma_f32 v[106:107], v[106:107], v[80:81], v[76:77] op_sel_hi:[1,1,0] neg_lo:[0,0,1] neg_hi:[0,0,1]
	v_mov_b32_e32 v108, v235
	v_mov_b32_e32 v109, v231
	v_mul_f32_e32 v76, v231, v81
	v_pk_mul_f32 v[92:93], v[230:231], v[78:79]
	v_pk_fma_f32 v[78:79], v[230:231], v[78:79], v[104:105] op_sel_hi:[0,1,1]
	v_pk_fma_f32 v[108:109], v[108:109], v[80:81], v[76:77] op_sel_hi:[1,1,0]
	v_sub_f32_e32 v78, v92, v104
	v_sub_f32_e32 v76, v74, v94
	v_mov_b32_e32 v80, v106
	v_mov_b32_e32 v81, v108
	v_mov_b32_e32 v92, v96
	v_mov_b32_e32 v93, v102

; __device__ __forceinline__ void store8(bf16_t* p, const f32x4& a, const f32x4& b) { u32x4 w; w.x = pk2(a[0], a[1]); w.y = pk2(a[2], a[3]); w.z = pk2(b[0], b[1]); w.w = pk2(b[2], b[3]); *(u32x4*)p = w; }
;     __device__ __forceinline__ void operator()(const f32x4 (&acc)[2][2][4][2], const pg8::Unit& u, int wr, int wc, int fr, int fq, int buf) const {
;     ...
;                     for (int bj = 0; bj < 2; ++bj) {
;                         const int hh = (grp >= 5) ? bj : (pn & 1) * 2 + bj;
;                         f32x4 v0 = acc[ai][bj][m][0], v1 = acc[ai][bj][m][1];
;                         if (hnorm) { const float r = rs[bj][ai][m];
; #pragma unroll
;                             for (int c = 0; c < 4; ++c) { v0[c] = v0[c] * r * gw[c]; v1[c] = v1[c] * r * gw[4 + c]; } }
;                         if (grp == 1) { v0 = v0 * 0.08838834764831845f; v1 = v1 * 0.08838834764831845f; }
;                         if (roped && lat) {
;                             f32x4 o0, o1;
;                             o0[0] = v0[0] * c4[0] - v0[1] * s4[0]; o0[1] = v0[1] * c4[0] + v0[0] * s4[0]; o0[2] = v0[2] * c4[1] - v0[3] * s4[1]; o0[3] = v0[3] * c4[1] + v0[2] * s4[1];
;                             o1[0] = v1[0] * c4[2] - v1[1] * s4[2]; o1[1] = v1[1] * c4[2] + v1[0] * s4[2]; o1[2] = v1[2] * c4[3] - v1[3] * s4[3]; o1[3] = v1[3] * c4[3] + v1[2] * s4[3];
;                             v0 = o0; v1 = o1;
;                         }
;                         bf16_t* dst = dbase + row * dld + 128 * hh + dloc;
;                         store8(dst, v0, v1);
.LBB0_1756:
	s_nop 0
	v_pk_mul_f32 v[76:77], v[68:69], s[56:57] op_sel_hi:[1,0]
	v_pk_mul_f32 v[78:79], v[66:67], s[56:57] op_sel_hi:[1,0]
	v_pk_mul_f32 v[80:81], v[72:73], s[56:57] op_sel_hi:[1,0]
	v_pk_mul_f32 v[90:91], v[70:71], s[56:57] op_sel_hi:[1,0]
	v_cndmask_b32_e64 v73, v73, v81, s[8:9]
	v_cndmask_b32_e64 v72, v72, v80, s[8:9]
	v_cndmask_b32_e64 v71, v71, v91, s[8:9]
	v_cndmask_b32_e64 v70, v70, v90, s[8:9]
	v_cndmask_b32_e64 v69, v69, v77, s[8:9]
	v_cndmask_b32_e64 v68, v68, v76, s[8:9]
	v_cndmask_b32_e64 v67, v67, v79, s[8:9]
	s_and_b64 vcc, exec, s[6:7]
	v_cndmask_b32_e64 v66, v66, v78, s[8:9]
	s_cbranch_vccnz .LBB0_1758
	v_pk_mul_f32 v[78:79], v[232:233], v[66:67] op_sel:[0,1] op_sel_hi:[0,0]
	v_pk_mul_f32 v[76:77], v[228:229], v[66:67]
	v_pk_fma_f32 v[66:67], v[228:229], v[66:67], v[78:79] op_sel_hi:[0,1,1]
	v_mov_b32_e32 v232, v229
	v_mul_f32_e32 v66, v233, v69
	v_pk_fma_f32 v[80:81], v[232:233], v[68:69], v[66:67] op_sel_hi:[1,1,0] neg_lo:[0,0,1] neg_hi:[0,0,1]
	v_mov_b32_e32 v228, v233
	v_mul_f32_e32 v66, v229, v69
	v_pk_fma_f32 v[228:229], v[228:229], v[68:69], v[66:67] op_sel_hi:[1,1,0]
	v_pk_mul_f32 v[232:233], v[234:235], v[70:71] op_sel:[0,1] op_sel_hi:[0,0]
	v_mov_b32_e32 v234, v231
	v_mul_f32_e32 v66, v235, v73
	v_pk_mul_f32 v[68:69], v[230:231], v[70:71]
	v_pk_fma_f32 v[70:71], v[230:231], v[70:71], v[232:233] op_sel_hi:[0,1,1]
	v_pk_fma_f32 v[90:91], v[234:235], v[72:73], v[66:67] op_sel_hi:[1,1,0] neg_lo:[0,0,1] neg_hi:[0,0,1]
	v_mov_b32_e32 v230, v235
	v_mul_f32_e32 v66, v231, v73
	v_pk_fma_f32 v[230:231], v[230:231], v[72:73], v[66:67] op_sel_hi:[1,1,0]
	v_sub_f32_e32 v70, v68, v232
	v_sub_f32_e32 v66, v76, v78
	v_mov_b32_e32 v72, v90
	v_mov_b32_e32 v73, v230
	v_mov_b32_e32 v68, v80
	v_mov_b32_e32 v69, v228
.LBB0_1758:
	v_cvt_pk_bf16_f32 v66, v66, v67
	v_cvt_pk_bf16_f32 v67, v68, v69
	v_cvt_pk_bf16_f32 v68, v70, v71
	v_cvt_pk_bf16_f32 v69, v72, v73
	global_store_dwordx4 v[74:75], v[66:69], off offset:256
	v_add_u32_e32 v74, 0x80, v164
.LBB0_1760:
	s_and_b64 vcc, exec, s[4:5]
	s_cbranch_vccnz .LBB0_1762
	v_pk_mul_f32 v[60:61], v[60:61], v[166:167] op_sel_hi:[1,0]
	v_pk_mul_f32 v[58:59], v[58:59], v[166:167] op_sel_hi:[1,0]
	v_pk_mul_f32 v[64:65], v[64:65], v[166:167] op_sel_hi:[1,0]
	v_pk_mul_f32 v[62:63], v[62:63], v[166:167] op_sel_hi:[1,0]
	v_pk_mul_f32 v[58:59], v[58:59], v[162:163]
	v_pk_mul_f32 v[60:61], v[60:61], v[98:99]
	v_pk_mul_f32 v[62:63], v[62:63], v[160:161]
	v_pk_mul_f32 v[64:65], v[64:65], v[100:101]
.LBB0_1762:
	v_pk_mul_f32 v[76:77], v[60:61], s[56:57] op_sel_hi:[1,0]
	v_pk_mul_f32 v[78:79], v[58:59], s[56:57] op_sel_hi:[1,0]
	v_pk_mul_f32 v[80:81], v[64:65], s[56:57] op_sel_hi:[1,0]
	v_pk_mul_f32 v[82:83], v[62:63], s[56:57] op_sel_hi:[1,0]
	v_cndmask_b32_e64 v65, v65, v81, s[8:9]
	v_cndmask_b32_e64 v64, v64, v80, s[8:9]
	v_cndmask_b32_e64 v63, v63, v83, s[8:9]
	v_cndmask_b32_e64 v62, v62, v82, s[8:9]
	v_cndmask_b32_e64 v77, v61, v77, s[8:9]
	v_cndmask_b32_e64 v76, v60, v76, s[8:9]
	v_cndmask_b32_e64 v61, v59, v79, s[8:9]
	s_and_b64 vcc, exec, s[6:7]
	v_cndmask_b32_e64 v60, v58, v78, s[8:9]
	s_cbranch_vccnz .LBB0_1764
	v_pk_mul_f32 v[78:79], v[240:241], v[60:61] op_sel:[0,1] op_sel_hi:[0,0]
	v_pk_mul_f32 v[58:59], v[236:237], v[60:61]
	v_pk_fma_f32 v[60:61], v[236:237], v[60:61], v[78:79] op_sel_hi:[0,1,1]
	v_mov_b32_e32 v80, v237
	v_mov_b32_e32 v81, v241
	v_mul_f32_e32 v60, v241, v77
	v_pk_fma_f32 v[80:81], v[80:81], v[76:77], v[60:61] op_sel_hi:[1,1,0] neg_lo:[0,0,1] neg_hi:[0,0,1]
	v_mov_b32_e32 v82, v241
	v_mov_b32_e32 v83, v237
	v_mul_f32_e32 v60, v237, v77
	v_pk_fma_f32 v[82:83], v[82:83], v[76:77], v[60:61] op_sel_hi:[1,1,0]
	v_mov_b32_e32 v86, v239
	v_mov_b32_e32 v87, v243
	v_mul_f32_e32 v60, v243, v65
	v_pk_mul_f32 v[84:85], v[242:243], v[62:63] op_sel:[0,1] op_sel_hi:[0,0]
	v_pk_fma_f32 v[86:87], v[86:87], v[64:65], v[60:61] op_sel_hi:[1,1,0] neg_lo:[0,0,1] neg_hi:[0,0,1]
	v_mov_b32_e32 v88, v243
	v_mov_b32_e32 v89, v239
	v_mul_f32_e32 v60, v239, v65
	v_pk_mul_f32 v[76:77], v[238:239], v[62:63]
	v_pk_fma_f32 v[62:63], v[238:239], v[62:63], v[84:85] op_sel_hi:[0,1,1]
	v_pk_fma_f32 v[88:89], v[88:89], v[64:65], v[60:61] op_sel_hi:[1,1,0]
	v_sub_f32_e32 v62, v76, v84
	v_sub_f32_e32 v60, v58, v78
	v_mov_b32_e32 v64, v86
	v_mov_b32_e32 v65, v88
	v_mov_b32_e32 v76, v80
	v_mov_b32_e32 v77, v82

; __device__ __forceinline__ void store8(bf16_t* p, const f32x4& a, const f32x4& b) { u32x4 w; w.x = pk2(a[0], a[1]); w.y = pk2(a[2], a[3]); w.z = pk2(b[0], b[1]); w.w = pk2(b[2], b[3]); *(u32x4*)p = w; }
;     __device__ __forceinline__ void operator()(const f32x4 (&acc)[2][2][4][2], const pg8::Unit& u, int wr, int wc, int fr, int fq, int buf) const {
;     ...
;                     for (int bj = 0; bj < 2; ++bj) {
;                         const int hh = (grp >= 5) ? bj : (pn & 1) * 2 + bj;
;                         f32x4 v0 = acc[ai][bj][m][0], v1 = acc[ai][bj][m][1];
;                         if (hnorm) { const float r = rs[bj][ai][m];
; #pragma unroll
;                             for (int c = 0; c < 4; ++c) { v0[c] = v0[c] * r * gw[c]; v1[c] = v1[c] * r * gw[4 + c]; } }
;                         if (grp == 1) { v0 = v0 * 0.08838834764831845f; v1 = v1 * 0.08838834764831845f; }
;                         if (roped && lat) {
;                             f32x4 o0, o1;
;                             o0[0] = v0[0] * c4[0] - v0[1] * s4[0]; o0[1] = v0[1] * c4[0] + v0[0] * s4[0]; o0[2] = v0[2] * c4[1] - v0[3] * s4[1]; o0[3] = v0[3] * c4[1] + v0[2] * s4[1];
;                             o1[0] = v1[0] * c4[2] - v1[1] * s4[2]; o1[1] = v1[1] * c4[2] + v1[0] * s4[2]; o1[2] = v1[2] * c4[3] - v1[3] * s4[3]; o1[3] = v1[3] * c4[3] + v1[2] * s4[3];
;                             v0 = o0; v1 = o1;
;                         }
;                         bf16_t* dst = dbase + row * dld + 128 * hh + dloc;
;                         store8(dst, v0, v1);
.LBB0_1766:
	s_nop 0
	v_pk_mul_f32 v[60:61], v[52:53], s[56:57] op_sel_hi:[1,0]
	v_pk_mul_f32 v[62:63], v[50:51], s[56:57] op_sel_hi:[1,0]
	v_pk_mul_f32 v[64:65], v[56:57], s[56:57] op_sel_hi:[1,0]
	v_pk_mul_f32 v[74:75], v[54:55], s[56:57] op_sel_hi:[1,0]
	v_cndmask_b32_e64 v57, v57, v65, s[8:9]
	v_cndmask_b32_e64 v56, v56, v64, s[8:9]
	v_cndmask_b32_e64 v55, v55, v75, s[8:9]
	v_cndmask_b32_e64 v54, v54, v74, s[8:9]
	v_cndmask_b32_e64 v53, v53, v61, s[8:9]
	v_cndmask_b32_e64 v52, v52, v60, s[8:9]
	v_cndmask_b32_e64 v51, v51, v63, s[8:9]
	s_and_b64 vcc, exec, s[6:7]
	v_cndmask_b32_e64 v50, v50, v62, s[8:9]
	s_cbranch_vccnz .LBB0_1768
	v_pk_mul_f32 v[62:63], v[240:241], v[50:51] op_sel:[0,1] op_sel_hi:[0,0]
	v_pk_mul_f32 v[60:61], v[236:237], v[50:51]
	v_pk_fma_f32 v[50:51], v[236:237], v[50:51], v[62:63] op_sel_hi:[0,1,1]
	v_mov_b32_e32 v240, v237
	v_mul_f32_e32 v50, v241, v53
	v_pk_fma_f32 v[64:65], v[240:241], v[52:53], v[50:51] op_sel_hi:[1,1,0] neg_lo:[0,0,1] neg_hi:[0,0,1]
	v_mov_b32_e32 v236, v241
	v_mul_f32_e32 v50, v237, v53
	v_pk_fma_f32 v[236:237], v[236:237], v[52:53], v[50:51] op_sel_hi:[1,1,0]
	v_pk_mul_f32 v[240:241], v[242:243], v[54:55] op_sel:[0,1] op_sel_hi:[0,0]
	v_mov_b32_e32 v242, v239
	v_mul_f32_e32 v50, v243, v57
	v_pk_mul_f32 v[52:53], v[238:239], v[54:55]
	v_pk_fma_f32 v[54:55], v[238:239], v[54:55], v[240:241] op_sel_hi:[0,1,1]
	v_pk_fma_f32 v[74:75], v[242:243], v[56:57], v[50:51] op_sel_hi:[1,1,0] neg_lo:[0,0,1] neg_hi:[0,0,1]
	v_mov_b32_e32 v238, v243
	v_mul_f32_e32 v50, v239, v57
	v_pk_fma_f32 v[238:239], v[238:239], v[56:57], v[50:51] op_sel_hi:[1,1,0]
	v_sub_f32_e32 v54, v52, v240
	v_sub_f32_e32 v50, v60, v62
	v_mov_b32_e32 v56, v74
	v_mov_b32_e32 v57, v238
	v_mov_b32_e32 v52, v64
	v_mov_b32_e32 v53, v236
.LBB0_1768:
	v_cvt_pk_bf16_f32 v50, v50, v51
	v_cvt_pk_bf16_f32 v51, v52, v53
	v_cvt_pk_bf16_f32 v52, v54, v55
	v_cvt_pk_bf16_f32 v53, v56, v57
	global_store_dwordx4 v[58:59], v[50:53], off offset:256
	v_add_u32_e32 v58, 0x90, v164
.LBB0_1770:
	s_and_b64 vcc, exec, s[4:5]
	s_cbranch_vccnz .LBB0_1772
	v_pk_mul_f32 v[44:45], v[44:45], v[166:167] op_sel:[0,1]
	v_pk_mul_f32 v[42:43], v[42:43], v[166:167] op_sel:[0,1]
	v_pk_mul_f32 v[48:49], v[48:49], v[166:167] op_sel:[0,1]
	v_pk_mul_f32 v[46:47], v[46:47], v[166:167] op_sel:[0,1]
	v_pk_mul_f32 v[42:43], v[42:43], v[162:163]
	v_pk_mul_f32 v[44:45], v[44:45], v[98:99]
	v_pk_mul_f32 v[46:47], v[46:47], v[160:161]
	v_pk_mul_f32 v[48:49], v[48:49], v[100:101]
.LBB0_1772:
	v_pk_mul_f32 v[60:61], v[44:45], s[56:57] op_sel_hi:[1,0]
	v_pk_mul_f32 v[62:63], v[42:43], s[56:57] op_sel_hi:[1,0]
	v_pk_mul_f32 v[64:65], v[48:49], s[56:57] op_sel_hi:[1,0]
	v_pk_mul_f32 v[66:67], v[46:47], s[56:57] op_sel_hi:[1,0]
	v_cndmask_b32_e64 v49, v49, v65, s[8:9]
	v_cndmask_b32_e64 v48, v48, v64, s[8:9]
	v_cndmask_b32_e64 v47, v47, v67, s[8:9]
	v_cndmask_b32_e64 v46, v46, v66, s[8:9]
	v_cndmask_b32_e64 v61, v45, v61, s[8:9]
	v_cndmask_b32_e64 v60, v44, v60, s[8:9]
	v_cndmask_b32_e64 v45, v43, v63, s[8:9]
	s_and_b64 vcc, exec, s[6:7]
	v_cndmask_b32_e64 v44, v42, v62, s[8:9]
	s_cbranch_vccnz .LBB0_1774
	v_pk_mul_f32 v[62:63], v[248:249], v[44:45] op_sel:[0,1] op_sel_hi:[0,0]
	v_pk_mul_f32 v[42:43], v[244:245], v[44:45]
	v_pk_fma_f32 v[44:45], v[244:245], v[44:45], v[62:63] op_sel_hi:[0,1,1]
	v_mov_b32_e32 v64, v245
	v_mov_b32_e32 v65, v249
	v_mul_f32_e32 v44, v249, v61
	v_pk_fma_f32 v[64:65], v[64:65], v[60:61], v[44:45] op_sel_hi:[1,1,0] neg_lo:[0,0,1] neg_hi:[0,0,1]
	v_mov_b32_e32 v66, v249
	v_mov_b32_e32 v67, v245
	v_mul_f32_e32 v44, v245, v61
	v_pk_fma_f32 v[66:67], v[66:67], v[60:61], v[44:45] op_sel_hi:[1,1,0]
	v_mov_b32_e32 v70, v247
	v_mov_b32_e32 v71, v251
	v_mul_f32_e32 v44, v251, v49
	v_pk_mul_f32 v[68:69], v[250:251], v[46:47] op_sel:[0,1] op_sel_hi:[0,0]
	v_pk_fma_f32 v[70:71], v[70:71], v[48:49], v[44:45] op_sel_hi:[1,1,0] neg_lo:[0,0,1] neg_hi:[0,0,1]
	v_mov_b32_e32 v72, v251
	v_mov_b32_e32 v73, v247
	v_mul_f32_e32 v44, v247, v49
	v_pk_mul_f32 v[60:61], v[246:247], v[46:47]
	v_pk_fma_f32 v[46:47], v[246:247], v[46:47], v[68:69] op_sel_hi:[0,1,1]
	v_pk_fma_f32 v[72:73], v[72:73], v[48:49], v[44:45] op_sel_hi:[1,1,0]
	v_sub_f32_e32 v46, v60, v68
	v_sub_f32_e32 v44, v42, v62
	v_mov_b32_e32 v48, v70
	v_mov_b32_e32 v49, v72
	v_mov_b32_e32 v60, v64
	v_mov_b32_e32 v61, v66

; __device__ __forceinline__ void store8(bf16_t* p, const f32x4& a, const f32x4& b) { u32x4 w; w.x = pk2(a[0], a[1]); w.y = pk2(a[2], a[3]); w.z = pk2(b[0], b[1]); w.w = pk2(b[2], b[3]); *(u32x4*)p = w; }
;     __device__ __forceinline__ void operator()(const f32x4 (&acc)[2][2][4][2], const pg8::Unit& u, int wr, int wc, int fr, int fq, int buf) const {
;     ...
;                     for (int bj = 0; bj < 2; ++bj) {
;                         const int hh = (grp >= 5) ? bj : (pn & 1) * 2 + bj;
;                         f32x4 v0 = acc[ai][bj][m][0], v1 = acc[ai][bj][m][1];
;                         if (hnorm) { const float r = rs[bj][ai][m];
; #pragma unroll
;                             for (int c = 0; c < 4; ++c) { v0[c] = v0[c] * r * gw[c]; v1[c] = v1[c] * r * gw[4 + c]; } }
;                         if (grp == 1) { v0 = v0 * 0.08838834764831845f; v1 = v1 * 0.08838834764831845f; }
;                         if (roped && lat) {
;                             f32x4 o0, o1;
;                             o0[0] = v0[0] * c4[0] - v0[1] * s4[0]; o0[1] = v0[1] * c4[0] + v0[0] * s4[0]; o0[2] = v0[2] * c4[1] - v0[3] * s4[1]; o0[3] = v0[3] * c4[1] + v0[2] * s4[1];
;                             o1[0] = v1[0] * c4[2] - v1[1] * s4[2]; o1[1] = v1[1] * c4[2] + v1[0] * s4[2]; o1[2] = v1[2] * c4[3] - v1[3] * s4[3]; o1[3] = v1[3] * c4[3] + v1[2] * s4[3];
;                             v0 = o0; v1 = o1;
;                         }
;                         bf16_t* dst = dbase + row * dld + 128 * hh + dloc;
;                         store8(dst, v0, v1);
.LBB0_1776:
	s_nop 0
	v_pk_mul_f32 v[44:45], v[36:37], s[56:57] op_sel_hi:[1,0]
	v_pk_mul_f32 v[46:47], v[34:35], s[56:57] op_sel_hi:[1,0]
	v_pk_mul_f32 v[48:49], v[40:41], s[56:57] op_sel_hi:[1,0]
	v_pk_mul_f32 v[58:59], v[38:39], s[56:57] op_sel_hi:[1,0]
	v_cndmask_b32_e64 v41, v41, v49, s[8:9]
	v_cndmask_b32_e64 v40, v40, v48, s[8:9]
	v_cndmask_b32_e64 v39, v39, v59, s[8:9]
	v_cndmask_b32_e64 v38, v38, v58, s[8:9]
	v_cndmask_b32_e64 v37, v37, v45, s[8:9]
	v_cndmask_b32_e64 v36, v36, v44, s[8:9]
	v_cndmask_b32_e64 v35, v35, v47, s[8:9]
	s_and_b64 vcc, exec, s[6:7]
	v_cndmask_b32_e64 v34, v34, v46, s[8:9]
	s_cbranch_vccnz .LBB0_1778
	v_pk_mul_f32 v[46:47], v[248:249], v[34:35] op_sel:[0,1] op_sel_hi:[0,0]
	v_pk_mul_f32 v[44:45], v[244:245], v[34:35]
	v_pk_fma_f32 v[34:35], v[244:245], v[34:35], v[46:47] op_sel_hi:[0,1,1]
	v_mov_b32_e32 v248, v245
	v_mul_f32_e32 v34, v249, v37
	v_pk_fma_f32 v[48:49], v[248:249], v[36:37], v[34:35] op_sel_hi:[1,1,0] neg_lo:[0,0,1] neg_hi:[0,0,1]
	v_mov_b32_e32 v244, v249
	v_mul_f32_e32 v34, v245, v37
	v_pk_fma_f32 v[244:245], v[244:245], v[36:37], v[34:35] op_sel_hi:[1,1,0]
	v_pk_mul_f32 v[248:249], v[250:251], v[38:39] op_sel:[0,1] op_sel_hi:[0,0]
	v_mov_b32_e32 v250, v247
	v_mul_f32_e32 v34, v251, v41
	v_pk_mul_f32 v[36:37], v[246:247], v[38:39]
	v_pk_fma_f32 v[38:39], v[246:247], v[38:39], v[248:249] op_sel_hi:[0,1,1]
	v_pk_fma_f32 v[58:59], v[250:251], v[40:41], v[34:35] op_sel_hi:[1,1,0] neg_lo:[0,0,1] neg_hi:[0,0,1]
	v_mov_b32_e32 v246, v251
	v_mul_f32_e32 v34, v247, v41
	v_pk_fma_f32 v[246:247], v[246:247], v[40:41], v[34:35] op_sel_hi:[1,1,0]
	v_sub_f32_e32 v38, v36, v248
	v_sub_f32_e32 v34, v44, v46
	v_mov_b32_e32 v40, v58
	v_mov_b32_e32 v41, v246
	v_mov_b32_e32 v36, v48
	v_mov_b32_e32 v37, v244
.LBB0_1778:
	v_cvt_pk_bf16_f32 v34, v34, v35
	v_cvt_pk_bf16_f32 v35, v36, v37
	v_cvt_pk_bf16_f32 v36, v38, v39
	v_cvt_pk_bf16_f32 v37, v40, v41
	global_store_dwordx4 v[42:43], v[34:37], off offset:256
	v_add_u32_e32 v42, 0xa0, v164
.LBB0_1780:
	s_and_b64 vcc, exec, s[4:5]
	s_cbranch_vccnz .LBB0_1782
	v_pk_mul_f32 v[28:29], v[28:29], v[156:157] op_sel_hi:[1,0]
	v_pk_mul_f32 v[26:27], v[26:27], v[156:157] op_sel_hi:[1,0]
	v_pk_mul_f32 v[32:33], v[32:33], v[156:157] op_sel_hi:[1,0]
	v_pk_mul_f32 v[30:31], v[30:31], v[156:157] op_sel_hi:[1,0]
	v_pk_mul_f32 v[26:27], v[26:27], v[162:163]
	v_pk_mul_f32 v[28:29], v[28:29], v[98:99]
	v_pk_mul_f32 v[30:31], v[30:31], v[160:161]
	v_pk_mul_f32 v[32:33], v[32:33], v[100:101]
.LBB0_1782:
	v_pk_mul_f32 v[44:45], v[28:29], s[56:57] op_sel_hi:[1,0]
	v_pk_mul_f32 v[46:47], v[26:27], s[56:57] op_sel_hi:[1,0]
	v_pk_mul_f32 v[48:49], v[32:33], s[56:57] op_sel_hi:[1,0]
	v_pk_mul_f32 v[50:51], v[30:31], s[56:57] op_sel_hi:[1,0]
	v_cndmask_b32_e64 v33, v33, v49, s[8:9]
	v_cndmask_b32_e64 v32, v32, v48, s[8:9]
	v_cndmask_b32_e64 v31, v31, v51, s[8:9]
	v_cndmask_b32_e64 v30, v30, v50, s[8:9]
	v_cndmask_b32_e64 v45, v29, v45, s[8:9]
	v_cndmask_b32_e64 v44, v28, v44, s[8:9]
	v_cndmask_b32_e64 v29, v27, v47, s[8:9]
	s_and_b64 vcc, exec, s[6:7]
	v_cndmask_b32_e64 v28, v26, v46, s[8:9]
	s_cbranch_vccnz .LBB0_1784
	s_waitcnt vmcnt(13)
	v_pk_mul_f32 v[46:47], v[208:209], v[28:29] op_sel:[0,1] op_sel_hi:[0,0]
	v_pk_mul_f32 v[26:27], v[204:205], v[28:29]
	v_pk_fma_f32 v[28:29], v[204:205], v[28:29], v[46:47] op_sel_hi:[0,1,1]
	v_mov_b32_e32 v48, v205
	v_mov_b32_e32 v49, v209
	v_mul_f32_e32 v28, v209, v45
	v_pk_fma_f32 v[48:49], v[48:49], v[44:45], v[28:29] op_sel_hi:[1,1,0] neg_lo:[0,0,1] neg_hi:[0,0,1]
	v_mov_b32_e32 v50, v209
	v_mov_b32_e32 v51, v205
	v_mul_f32_e32 v28, v205, v45
	v_pk_fma_f32 v[50:51], v[50:51], v[44:45], v[28:29] op_sel_hi:[1,1,0]
	v_mov_b32_e32 v54, v207
	v_mov_b32_e32 v55, v211
	v_mul_f32_e32 v28, v211, v33
	v_pk_mul_f32 v[52:53], v[210:211], v[30:31] op_sel:[0,1] op_sel_hi:[0,0]
	v_pk_fma_f32 v[54:55], v[54:55], v[32:33], v[28:29] op_sel_hi:[1,1,0] neg_lo:[0,0,1] neg_hi:[0,0,1]
	v_mov_b32_e32 v56, v211
	v_mov_b32_e32 v57, v207
	v_mul_f32_e32 v28, v207, v33
	v_pk_mul_f32 v[44:45], v[206:207], v[30:31]
	v_pk_fma_f32 v[30:31], v[206:207], v[30:31], v[52:53] op_sel_hi:[0,1,1]
	v_pk_fma_f32 v[56:57], v[56:57], v[32:33], v[28:29] op_sel_hi:[1,1,0]
	v_sub_f32_e32 v30, v44, v52
	v_sub_f32_e32 v28, v26, v46
	v_mov_b32_e32 v32, v54
	v_mov_b32_e32 v33, v56
	v_mov_b32_e32 v44, v48
	v_mov_b32_e32 v45, v50

; __device__ __forceinline__ void store8(bf16_t* p, const f32x4& a, const f32x4& b) { u32x4 w; w.x = pk2(a[0], a[1]); w.y = pk2(a[2], a[3]); w.z = pk2(b[0], b[1]); w.w = pk2(b[2], b[3]); *(u32x4*)p = w; }
;     __device__ __forceinline__ void operator()(const f32x4 (&acc)[2][2][4][2], const pg8::Unit& u, int wr, int wc, int fr, int fq, int buf) const {
;     ...
;                     for (int bj = 0; bj < 2; ++bj) {
;                         const int hh = (grp >= 5) ? bj : (pn & 1) * 2 + bj;
;                         f32x4 v0 = acc[ai][bj][m][0], v1 = acc[ai][bj][m][1];
;                         if (hnorm) { const float r = rs[bj][ai][m];
; #pragma unroll
;                             for (int c = 0; c < 4; ++c) { v0[c] = v0[c] * r * gw[c]; v1[c] = v1[c] * r * gw[4 + c]; } }
;                         if (grp == 1) { v0 = v0 * 0.08838834764831845f; v1 = v1 * 0.08838834764831845f; }
;                         if (roped && lat) {
;                             f32x4 o0, o1;
;                             o0[0] = v0[0] * c4[0] - v0[1] * s4[0]; o0[1] = v0[1] * c4[0] + v0[0] * s4[0]; o0[2] = v0[2] * c4[1] - v0[3] * s4[1]; o0[3] = v0[3] * c4[1] + v0[2] * s4[1];
;                             o1[0] = v1[0] * c4[2] - v1[1] * s4[2]; o1[1] = v1[1] * c4[2] + v1[0] * s4[2]; o1[2] = v1[2] * c4[3] - v1[3] * s4[3]; o1[3] = v1[3] * c4[3] + v1[2] * s4[3];
;                             v0 = o0; v1 = o1;
;                         }
;                         bf16_t* dst = dbase + row * dld + 128 * hh + dloc;
;                         store8(dst, v0, v1);
.LBB0_1786:
	s_nop 0
	v_pk_mul_f32 v[28:29], v[20:21], s[56:57] op_sel_hi:[1,0]
	v_pk_mul_f32 v[30:31], v[18:19], s[56:57] op_sel_hi:[1,0]
	v_pk_mul_f32 v[32:33], v[24:25], s[56:57] op_sel_hi:[1,0]
	v_pk_mul_f32 v[42:43], v[22:23], s[56:57] op_sel_hi:[1,0]
	v_cndmask_b32_e64 v25, v25, v33, s[8:9]
	v_cndmask_b32_e64 v24, v24, v32, s[8:9]
	v_cndmask_b32_e64 v23, v23, v43, s[8:9]
	v_cndmask_b32_e64 v22, v22, v42, s[8:9]
	v_cndmask_b32_e64 v21, v21, v29, s[8:9]
	v_cndmask_b32_e64 v20, v20, v28, s[8:9]
	v_cndmask_b32_e64 v19, v19, v31, s[8:9]
	s_and_b64 vcc, exec, s[6:7]
	v_cndmask_b32_e64 v18, v18, v30, s[8:9]
	s_cbranch_vccnz .LBB0_1788
	v_pk_mul_f32 v[30:31], v[208:209], v[18:19] op_sel:[0,1] op_sel_hi:[0,0]
	v_pk_mul_f32 v[28:29], v[204:205], v[18:19]
	v_pk_fma_f32 v[18:19], v[204:205], v[18:19], v[30:31] op_sel_hi:[0,1,1]
	v_mov_b32_e32 v208, v205
	v_mul_f32_e32 v18, v209, v21
	v_pk_fma_f32 v[32:33], v[208:209], v[20:21], v[18:19] op_sel_hi:[1,1,0] neg_lo:[0,0,1] neg_hi:[0,0,1]
	v_mov_b32_e32 v204, v209
	v_mul_f32_e32 v18, v205, v21
	v_pk_fma_f32 v[204:205], v[204:205], v[20:21], v[18:19] op_sel_hi:[1,1,0]
	v_pk_mul_f32 v[208:209], v[210:211], v[22:23] op_sel:[0,1] op_sel_hi:[0,0]
	v_mov_b32_e32 v210, v207
	v_mul_f32_e32 v18, v211, v25
	v_pk_mul_f32 v[20:21], v[206:207], v[22:23]
	v_pk_fma_f32 v[22:23], v[206:207], v[22:23], v[208:209] op_sel_hi:[0,1,1]
	v_pk_fma_f32 v[42:43], v[210:211], v[24:25], v[18:19] op_sel_hi:[1,1,0] neg_lo:[0,0,1] neg_hi:[0,0,1]
	v_mov_b32_e32 v206, v211
	v_mul_f32_e32 v18, v207, v25
	v_pk_fma_f32 v[206:207], v[206:207], v[24:25], v[18:19] op_sel_hi:[1,1,0]
	v_sub_f32_e32 v22, v20, v208
	v_sub_f32_e32 v18, v28, v30
	v_mov_b32_e32 v24, v42
	v_mov_b32_e32 v25, v206
	v_mov_b32_e32 v20, v32
	v_mov_b32_e32 v21, v204
.LBB0_1788:
	v_cvt_pk_bf16_f32 v18, v18, v19
	v_cvt_pk_bf16_f32 v19, v20, v21
	v_cvt_pk_bf16_f32 v20, v22, v23
	v_cvt_pk_bf16_f32 v21, v24, v25
	global_store_dwordx4 v[26:27], v[18:21], off offset:256
	v_add_u32_e32 v26, 0xb0, v164
.LBB0_1790:
	s_and_b64 vcc, exec, s[4:5]
	s_cbranch_vccnz .LBB0_1792
	v_pk_mul_f32 v[12:13], v[12:13], v[156:157] op_sel:[0,1]
	v_pk_mul_f32 v[10:11], v[10:11], v[156:157] op_sel:[0,1]
	v_pk_mul_f32 v[16:17], v[16:17], v[156:157] op_sel:[0,1]
	v_pk_mul_f32 v[14:15], v[14:15], v[156:157] op_sel:[0,1]
	v_pk_mul_f32 v[10:11], v[10:11], v[162:163]
	v_pk_mul_f32 v[12:13], v[12:13], v[98:99]
	v_pk_mul_f32 v[14:15], v[14:15], v[160:161]
	v_pk_mul_f32 v[16:17], v[16:17], v[100:101]
.LBB0_1792:
	v_pk_mul_f32 v[28:29], v[12:13], s[56:57] op_sel_hi:[1,0]
	v_pk_mul_f32 v[30:31], v[10:11], s[56:57] op_sel_hi:[1,0]
	v_pk_mul_f32 v[32:33], v[16:17], s[56:57] op_sel_hi:[1,0]
	v_pk_mul_f32 v[34:35], v[14:15], s[56:57] op_sel_hi:[1,0]
	v_cndmask_b32_e64 v17, v17, v33, s[8:9]
	v_cndmask_b32_e64 v16, v16, v32, s[8:9]
	v_cndmask_b32_e64 v15, v15, v35, s[8:9]
	v_cndmask_b32_e64 v14, v14, v34, s[8:9]
	v_cndmask_b32_e64 v29, v13, v29, s[8:9]
	v_cndmask_b32_e64 v28, v12, v28, s[8:9]
	v_cndmask_b32_e64 v13, v11, v31, s[8:9]
	s_and_b64 vcc, exec, s[6:7]
	v_cndmask_b32_e64 v12, v10, v30, s[8:9]
	s_cbranch_vccnz .LBB0_1794
	s_waitcnt vmcnt(11)
	v_pk_mul_f32 v[30:31], v[216:217], v[12:13] op_sel:[0,1] op_sel_hi:[0,0]
	v_pk_mul_f32 v[10:11], v[212:213], v[12:13]
	v_pk_fma_f32 v[12:13], v[212:213], v[12:13], v[30:31] op_sel_hi:[0,1,1]
	v_mov_b32_e32 v32, v213
	v_mov_b32_e32 v33, v217
	v_mul_f32_e32 v12, v217, v29
	v_pk_fma_f32 v[32:33], v[32:33], v[28:29], v[12:13] op_sel_hi:[1,1,0] neg_lo:[0,0,1] neg_hi:[0,0,1]
	v_mov_b32_e32 v34, v217
	v_mov_b32_e32 v35, v213
	v_mul_f32_e32 v12, v213, v29
	v_pk_fma_f32 v[34:35], v[34:35], v[28:29], v[12:13] op_sel_hi:[1,1,0]
	v_mov_b32_e32 v38, v215
	v_mov_b32_e32 v39, v219
	v_mul_f32_e32 v12, v219, v17
	v_pk_mul_f32 v[36:37], v[218:219], v[14:15] op_sel:[0,1] op_sel_hi:[0,0]
	v_pk_fma_f32 v[38:39], v[38:39], v[16:17], v[12:13] op_sel_hi:[1,1,0] neg_lo:[0,0,1] neg_hi:[0,0,1]
	v_mov_b32_e32 v40, v219
	v_mov_b32_e32 v41, v215
	v_mul_f32_e32 v12, v215, v17
	v_pk_mul_f32 v[28:29], v[214:215], v[14:15]
	v_pk_fma_f32 v[14:15], v[214:215], v[14:15], v[36:37] op_sel_hi:[0,1,1]
	v_pk_fma_f32 v[40:41], v[40:41], v[16:17], v[12:13] op_sel_hi:[1,1,0]
	v_sub_f32_e32 v14, v28, v36
	v_sub_f32_e32 v12, v10, v30
	v_mov_b32_e32 v16, v38
	v_mov_b32_e32 v17, v40
	v_mov_b32_e32 v28, v32
	v_mov_b32_e32 v29, v34

; __device__ __forceinline__ void store8(bf16_t* p, const f32x4& a, const f32x4& b) { u32x4 w; w.x = pk2(a[0], a[1]); w.y = pk2(a[2], a[3]); w.z = pk2(b[0], b[1]); w.w = pk2(b[2], b[3]); *(u32x4*)p = w; }
;     __device__ __forceinline__ void operator()(const f32x4 (&acc)[2][2][4][2], const pg8::Unit& u, int wr, int wc, int fr, int fq, int buf) const {
;     ...
;                     for (int bj = 0; bj < 2; ++bj) {
;                         const int hh = (grp >= 5) ? bj : (pn & 1) * 2 + bj;
;                         f32x4 v0 = acc[ai][bj][m][0], v1 = acc[ai][bj][m][1];
;                         if (hnorm) { const float r = rs[bj][ai][m];
; #pragma unroll
;                             for (int c = 0; c < 4; ++c) { v0[c] = v0[c] * r * gw[c]; v1[c] = v1[c] * r * gw[4 + c]; } }
;                         if (grp == 1) { v0 = v0 * 0.08838834764831845f; v1 = v1 * 0.08838834764831845f; }
;                         if (roped && lat) {
;                             f32x4 o0, o1;
;                             o0[0] = v0[0] * c4[0] - v0[1] * s4[0]; o0[1] = v0[1] * c4[0] + v0[0] * s4[0]; o0[2] = v0[2] * c4[1] - v0[3] * s4[1]; o0[3] = v0[3] * c4[1] + v0[2] * s4[1];
;                             o1[0] = v1[0] * c4[2] - v1[1] * s4[2]; o1[1] = v1[1] * c4[2] + v1[0] * s4[2]; o1[2] = v1[2] * c4[3] - v1[3] * s4[3]; o1[3] = v1[3] * c4[3] + v1[2] * s4[3];
;                             v0 = o0; v1 = o1;
;                         }
;                         bf16_t* dst = dbase + row * dld + 128 * hh + dloc;
;                         store8(dst, v0, v1);
.LBB0_1796:
	s_nop 0
	v_pk_mul_f32 v[14:15], v[8:9], s[56:57] op_sel_hi:[1,0]
	v_pk_mul_f32 v[16:17], v[6:7], s[56:57] op_sel_hi:[1,0]
	v_pk_mul_f32 v[12:13], v[4:5], s[56:57] op_sel_hi:[1,0]
	v_pk_mul_f32 v[26:27], v[2:3], s[56:57] op_sel_hi:[1,0]
	v_cndmask_b32_e64 v13, v5, v13, s[8:9]
	v_cndmask_b32_e64 v12, v4, v12, s[8:9]
	v_cndmask_b32_e64 v3, v3, v27, s[8:9]
	v_cndmask_b32_e64 v2, v2, v26, s[8:9]
	v_cndmask_b32_e64 v9, v9, v15, s[8:9]
	v_cndmask_b32_e64 v8, v8, v14, s[8:9]
	v_cndmask_b32_e64 v5, v7, v17, s[8:9]
	s_and_b64 vcc, exec, s[6:7]
	v_cndmask_b32_e64 v4, v6, v16, s[8:9]
	s_cbranch_vccnz .LBB0_1798
	v_pk_mul_f32 v[14:15], v[216:217], v[4:5] op_sel:[0,1] op_sel_hi:[0,0]
	v_pk_mul_f32 v[6:7], v[212:213], v[4:5]
	v_pk_fma_f32 v[4:5], v[212:213], v[4:5], v[14:15] op_sel_hi:[0,1,1]
	v_mov_b32_e32 v216, v213
	v_mul_f32_e32 v4, v217, v9
	v_pk_fma_f32 v[16:17], v[216:217], v[8:9], v[4:5] op_sel_hi:[1,1,0] neg_lo:[0,0,1] neg_hi:[0,0,1]
	v_mov_b32_e32 v212, v217
	v_mul_f32_e32 v4, v213, v9
	v_pk_mul_f32 v[216:217], v[218:219], v[2:3] op_sel:[0,1] op_sel_hi:[0,0]
	v_pk_fma_f32 v[212:213], v[212:213], v[8:9], v[4:5] op_sel_hi:[1,1,0]
	v_pk_mul_f32 v[8:9], v[214:215], v[2:3]
	v_pk_fma_f32 v[2:3], v[214:215], v[2:3], v[216:217] op_sel_hi:[0,1,1]
	v_mov_b32_e32 v218, v215
	v_mul_f32_e32 v2, v219, v13
	v_pk_fma_f32 v[26:27], v[218:219], v[12:13], v[2:3] op_sel_hi:[1,1,0] neg_lo:[0,0,1] neg_hi:[0,0,1]
	v_mov_b32_e32 v214, v219
	v_mul_f32_e32 v2, v215, v13
	v_pk_fma_f32 v[214:215], v[214:215], v[12:13], v[2:3] op_sel_hi:[1,1,0]
	v_sub_f32_e32 v2, v8, v216
	v_sub_f32_e32 v4, v6, v14
	v_mov_b32_e32 v12, v26
	v_mov_b32_e32 v13, v214
	v_mov_b32_e32 v8, v16
	v_mov_b32_e32 v9, v212
